# XCD-local barrier release without L2 write-back for the 5 per-layer barriers whose producer and consumer rows belong to one XCD group (guarded by start-up group-to-XCC bijection check); global barrier
# speedup vs baseline: 1.0117x; 1.0117x over previous
_Z14fwd_megakernel1P:
	s_load_dwordx8 s[4:11], s[0:1], 0x100
	s_load_dword s52, s[0:1], 0x138
	s_load_dwordx4 s[88:91], s[0:1], 0x120
	s_load_dwordx2 s[96:97], s[0:1], 0x130
	v_writelane_b32 v252, s2, 0
	s_add_u32 s2, s0, 0x130
	v_and_b32_e32 v228, 0x3ff, v0
	s_waitcnt lgkmcnt(0)
	v_writelane_b32 v252, s4, 1
	s_addc_u32 s3, s1, 0
	s_nop 0
	v_writelane_b32 v252, s5, 2
	v_writelane_b32 v252, s6, 3
	v_writelane_b32 v252, s7, 4
	v_writelane_b32 v252, s8, 5
	v_writelane_b32 v252, s9, 6
	v_writelane_b32 v252, s10, 7
	v_writelane_b32 v252, s11, 8
	v_cmp_eq_u32_e64 s[10:11], 0, v228
	s_and_saveexec_b64 s[4:5], s[10:11]
	v_mov_b32_e32 v2, 0
	v_mov_b32_e32 v3, v2
	v_mov_b32_e32 v4, v2
	v_mov_b32_e32 v5, v2
	ds_write_b128 v2, v[2:5] offset:61440
	s_or_b64 exec, exec, s[4:5]
	s_add_u32 s4, s90, 0x1794c000
	s_addc_u32 s5, s91, 0
	v_writelane_b32 v252, s4, 9
	s_waitcnt lgkmcnt(0)
	s_barrier
	v_writelane_b32 v252, s5, 10
	v_writelane_b32 v252, s10, 11
	s_getreg_b32 s8, hwreg(HW_REG_XCC_ID, 0, 4)
	s_nop 0
	v_writelane_b32 v252, s11, 12
	s_and_saveexec_b64 s[4:5], s[10:11]
	s_cbranch_execz .LBB0_5
	s_mov_b64 s[6:7], exec
	v_mbcnt_lo_u32_b32 v1, s6, 0
	v_mbcnt_hi_u32_b32 v1, s7, v1
	v_cmp_eq_u32_e32 vcc, 0, v1
	s_and_b64 s[10:11], exec, vcc
	s_mov_b64 exec, s[10:11]
	s_cbranch_execz .LBB0_5
	v_readlane_b32 s9, v252, 0
	s_and_b32 s9, s9, 7
	s_lshl_b32 s9, s9, 4
	s_or_b32 s9, s9, s8
	s_lshr_b32 s12, s9, 5
	s_lshl_b32 s12, s12, 2
	s_and_b32 s9, s9, 31
	s_lshl_b32 s9, 1, s9
	v_mov_b32_e32 v3, s9
	v_mov_b32_e32 v4, s12
	v_readlane_b32 s12, v252, 9
	v_readlane_b32 s13, v252, 10
	s_nop 4
	global_atomic_or v4, v3, s[12:13] offset:768
	s_lshl_b32 s8, s8, 8
	s_bcnt1_i32_b64 s6, s[6:7]
	s_and_b32 s8, s8, 0xf00
	v_mov_b32_e32 v2, s6
	v_readlane_b32 s6, v252, 9
	v_mov_b32_e32 v1, s8
	v_readlane_b32 s7, v252, 10
	s_nop 4
	global_atomic_add v1, v2, s[6:7] offset:1024

.LBB0_188:
	s_or_b64 exec, exec, s[0:1]
	s_add_u32 s44, s90, 0x9148000
	s_addc_u32 s45, s91, 0
	s_add_u32 s40, s90, 0x7148000
	s_addc_u32 s41, s91, 0
	s_ashr_i32 s4, s96, 3
	s_add_u32 s42, s90, 0x1794c200
	s_addc_u32 s43, s91, 0
	s_add_u32 s56, s90, 0x1794c400
	s_addc_u32 s57, s91, 0
	s_add_u32 s58, s90, 0x1794c500
	s_addc_u32 s59, s91, 0
	s_add_u32 s60, s90, 0x1794c600
	s_addc_u32 s61, s91, 0
	s_add_u32 s62, s90, 0x1794c700
	s_addc_u32 s63, s91, 0
	s_add_u32 s64, s90, 0x1794c800
	s_addc_u32 s65, s91, 0
	s_add_u32 s26, s90, 0x1794c900
	s_addc_u32 s27, s91, 0
	s_add_u32 s0, s90, 0x1794ca00
	s_addc_u32 s1, s91, 0
	v_writelane_b32 v253, s0, 20
	v_readlane_b32 s2, v252, 0
	s_mul_i32 s68, s97, s96
	v_writelane_b32 v253, s1, 21
	s_add_u32 s0, s90, 0x1794cb00
	s_addc_u32 s1, s91, 0
	v_writelane_b32 v253, s0, 22
	s_mul_i32 s68, s68, s52
	v_mov_b32_e32 v197, 0
	v_writelane_b32 v253, s1, 23
	s_add_u32 s0, s90, 0x1794cc00
	s_addc_u32 s1, s91, 0
	v_writelane_b32 v253, s0, 24
	v_mov_b32_e32 v229, 0x358637bd
	v_mov_b32_e32 v234, 0x1000
	v_writelane_b32 v253, s1, 25
	s_add_u32 s0, s90, 0x1794cd00
	s_addc_u32 s1, s91, 0
	v_writelane_b32 v253, s0, 26
	v_mov_b32_e32 v236, 0x2000
	v_mov_b32_e32 v235, 0xf149f2ca
	v_writelane_b32 v253, s1, 27
	s_add_u32 s0, s90, 0x1794ce00
	s_addc_u32 s1, s91, 0
	v_writelane_b32 v253, s0, 28
	v_mov_b32_e32 v237, 0x41b17218
	s_movk_i32 s28, 0x1800
	v_writelane_b32 v253, s1, 29
	s_add_u32 s0, s90, 0x1794cf00
	s_addc_u32 s1, s91, 0
	v_writelane_b32 v253, s0, 30
	s_movk_i32 s22, 0x1fff
	s_mov_b32 s69, 0x800000
	v_writelane_b32 v253, s1, 31
	s_add_u32 s0, s90, 0x1794d000
	s_addc_u32 s1, s91, 0
	v_writelane_b32 v253, s0, 32
	s_movk_i32 s70, 0x1a00
	s_mov_b32 s30, 0xf149f2ca
	v_writelane_b32 v253, s1, 33
	s_add_u32 s0, s90, 0x1794d100
	s_addc_u32 s1, s91, 0
	v_writelane_b32 v253, s0, 34
	s_movk_i32 s47, 0x1000
	s_mov_b32 s71, 0xbfb8aa3b
	v_writelane_b32 v253, s1, 35
	s_add_u32 s0, s90, 0x1794d200
	s_addc_u32 s1, s91, 0
	v_writelane_b32 v253, s0, 36
	s_mov_b32 s38, 0x3f317217
	s_mov_b32 s39, 0x7f800000
	v_writelane_b32 v253, s1, 37
	s_add_u32 s0, s90, 0x1794d300
	s_addc_u32 s1, s91, 0
	v_writelane_b32 v253, s0, 38
	s_movk_i32 s46, 0x1600
	s_mov_b32 s51, 0
	v_writelane_b32 v253, s1, 39
	s_add_u32 s0, s90, 0x1794f400
	s_addc_u32 s1, s91, 0
	v_writelane_b32 v253, s0, 40
	s_mov_b32 s52, 0x3c800000
	s_waitcnt lgkmcnt(0)
	v_writelane_b32 v253, s1, 41
	s_add_u32 s0, s90, 0x1794f500
	s_addc_u32 s1, s91, 0
	s_lshr_b32 s53, s96, 3
	v_writelane_b32 v253, s0, 42
	s_cmpk_lt_u32 s2, 0xc00
	s_barrier
	v_writelane_b32 v253, s1, 43
	s_cselect_b64 s[0:1], -1, 0
	v_writelane_b32 v253, s0, 44
	s_lshr_b32 s3, s2, 3
	s_nop 0
	v_writelane_b32 v253, s1, 45
	s_lshl_b32 s0, s2, 4
	s_and_b32 s0, s0, 0x70
	s_cmpk_lt_u32 s2, 0x680
	v_writelane_b32 v253, s0, 46
	s_cselect_b64 s[0:1], -1, 0
	v_writelane_b32 v253, s0, 47
	s_nop 1
	v_writelane_b32 v253, s1, 48
	s_add_u32 s6, s90, 0x1794c300
	s_addc_u32 s7, s91, 0
	v_mov_b32_e32 v1, 0
	global_load_dwordx4 v[4:7], v1, s[6:7] sc1
	s_waitcnt vmcnt(0)
	v_readfirstlane_b32 s6, v4
	v_readfirstlane_b32 s7, v5
	v_readfirstlane_b32 s8, v6
	v_readfirstlane_b32 s9, v7
	s_mov_b32 s10, 0
	s_mov_b32 s11, 1
	s_and_b32 s5, s6, 0xffff
	s_or_b32 s10, s10, s5
	s_bcnt1_i32_b32 s5, s5
	s_cmp_eq_u32 s5, 1
	s_cselect_b32 s11, s11, 0
	s_lshr_b32 s5, s6, 16
	s_or_b32 s10, s10, s5
	s_bcnt1_i32_b32 s5, s5
	s_cmp_eq_u32 s5, 1
	s_cselect_b32 s11, s11, 0
	s_and_b32 s5, s7, 0xffff
	s_or_b32 s10, s10, s5
	s_bcnt1_i32_b32 s5, s5
	s_cmp_eq_u32 s5, 1
	s_cselect_b32 s11, s11, 0
	s_lshr_b32 s5, s7, 16
	s_or_b32 s10, s10, s5
	s_bcnt1_i32_b32 s5, s5
	s_cmp_eq_u32 s5, 1
	s_cselect_b32 s11, s11, 0
	s_and_b32 s5, s8, 0xffff
	s_or_b32 s10, s10, s5
	s_bcnt1_i32_b32 s5, s5
	s_cmp_eq_u32 s5, 1
	s_cselect_b32 s11, s11, 0
	s_lshr_b32 s5, s8, 16
	s_or_b32 s10, s10, s5
	s_bcnt1_i32_b32 s5, s5
	s_cmp_eq_u32 s5, 1
	s_cselect_b32 s11, s11, 0
	s_and_b32 s5, s9, 0xffff
	s_or_b32 s10, s10, s5
	s_bcnt1_i32_b32 s5, s5
	s_cmp_eq_u32 s5, 1
	s_cselect_b32 s11, s11, 0
	s_lshr_b32 s5, s9, 16
	s_or_b32 s10, s10, s5
	s_bcnt1_i32_b32 s5, s5
	s_cmp_eq_u32 s5, 1
	s_cselect_b32 s11, s11, 0
	s_bcnt1_i32_b32 s5, s10
	s_cmp_eq_u32 s5, 8
	s_cselect_b32 s11, s11, 0
	s_nop 0
	v_writelane_b32 v255, s11, 12
	s_lshl_b32 s0, s2, 3
	s_and_b32 s33, s0, 56
	s_add_i32 s0, s96, 0xbff
	v_writelane_b32 v253, s0, 49
	s_ashr_i32 s0, s96, 1
	s_add_u32 s94, s90, 0x7048000
	s_addc_u32 s95, s91, 0
	s_add_u32 s48, s90, 0x13948000
	s_addc_u32 s49, s91, 0
	s_add_u32 s92, s90, 0xf948000
	s_addc_u32 s93, s91, 0
	s_cmpk_lt_i32 s96, 0x101
	v_writelane_b32 v253, s0, 50
	s_cselect_b64 s[0:1], -1, 0
	v_writelane_b32 v253, s0, 51
	s_nop 1
	v_writelane_b32 v253, s1, 52
	s_add_u32 s0, s88, 0x8000000
	v_writelane_b32 v253, s0, 53
	s_addc_u32 s0, s89, 0
	v_writelane_b32 v253, s0, 54
	s_add_i32 s0, s96, 0xffffff80
	v_writelane_b32 v253, s0, 55
	s_add_u32 s0, s90, 0x7148400
	s_addc_u32 s1, s91, 0
	v_writelane_b32 v253, s0, 56
	s_cmpk_lt_u32 s2, 0xb00
	s_nop 0
	v_writelane_b32 v253, s1, 57
	s_cselect_b64 s[0:1], -1, 0
	v_writelane_b32 v253, s0, 58
	s_cmpk_lt_u32 s2, 0x200
	s_nop 0
	v_writelane_b32 v253, s1, 59
	s_cselect_b64 s[0:1], -1, 0
	v_writelane_b32 v253, s0, 60
	s_cmp_lt_u32 s33, 32
	s_nop 0
	v_writelane_b32 v253, s1, 61
	s_cselect_b64 s[0:1], -1, 0
	v_writelane_b32 v253, s0, 62
	s_lshl_b32 s35, s4, 2
	s_nop 0
	v_writelane_b32 v253, s1, 63
	s_abs_i32 s0, s96
	v_cvt_f32_u32_e32 v0, s0
	s_ashr_i32 s1, s96, 31
	v_writelane_b32 v254, s1, 0
	v_writelane_b32 v254, s0, 1
	v_rcp_iflag_f32_e32 v0, v0
	s_sub_i32 s0, 0, s0
	v_mul_f32_e32 v0, 0x4f7ffffe, v0
	v_cvt_u32_f32_e32 v0, v0
	s_nop 0
	v_readfirstlane_b32 s1, v0
	s_mul_i32 s0, s0, s1
	s_mul_hi_u32 s0, s1, s0
	s_add_i32 s0, s1, s0
	v_writelane_b32 v254, s0, 2
	s_add_u32 s0, s90, 0x7148080
	v_writelane_b32 v254, s4, 3
	s_addc_u32 s1, s91, 0
	v_writelane_b32 v254, s0, 4
	s_nop 1
	v_writelane_b32 v254, s1, 5
	s_lshl_b32 s0, s2, 11
	s_and_b32 s0, s0, 0x3800
	s_or_b32 s1, s0, 32
	v_writelane_b32 v254, s1, 6
	s_or_b32 s1, s0, 64
	v_writelane_b32 v254, s1, 7
	s_or_b32 s1, s0, 0x60
	s_add_u32 s4, s90, 0x1100080
	v_writelane_b32 v254, s1, 8
	s_addc_u32 s5, s91, 0
	v_writelane_b32 v254, s4, 9
	s_and_b32 s1, s2, -8
	s_nop 0
	v_writelane_b32 v254, s5, 10
	v_writelane_b32 v254, s1, 11
	s_and_b32 s1, s96, -8
	v_writelane_b32 v254, s1, 12
	s_or_b32 s1, s0, 0x80
	v_writelane_b32 v254, s1, 13
	s_or_b32 s1, s0, 0xa0
	v_writelane_b32 v254, s1, 14
	s_or_b32 s1, s0, 0xc0
	v_writelane_b32 v254, s1, 15
	v_writelane_b32 v254, s0, 16
	s_or_b32 s0, s0, 0xe0
	v_writelane_b32 v254, s0, 17
	s_add_u32 s0, s90, 0x80
	v_writelane_b32 v254, s0, 18
	s_addc_u32 s0, s91, 0
	v_writelane_b32 v254, s0, 19
	v_writelane_b32 v254, s3, 20
	s_lshl_b32 s0, s3, 4
	v_writelane_b32 v254, s0, 21
	s_lshl_b32 s0, s53, 4
	v_writelane_b32 v254, s0, 22
	s_add_u32 s0, s90, 0x2100080
	s_addc_u32 s1, s91, 0
	v_writelane_b32 v254, s0, 23
	s_mov_b64 s[2:3], 0
	s_nop 0
	v_writelane_b32 v254, s1, 24
	v_writelane_b32 v254, s35, 25
	v_writelane_b32 v254, s40, 26
	s_nop 1
	v_writelane_b32 v254, s41, 27
	v_writelane_b32 v254, s42, 28
	s_nop 1
	v_writelane_b32 v254, s43, 29
	v_writelane_b32 v254, s56, 30
	s_nop 1
	v_writelane_b32 v254, s57, 31
	v_writelane_b32 v254, s58, 32
	s_nop 1
	v_writelane_b32 v254, s59, 33
	v_writelane_b32 v254, s60, 34
	s_nop 1
	v_writelane_b32 v254, s61, 35
	v_writelane_b32 v254, s62, 36
	s_nop 1
	v_writelane_b32 v254, s63, 37
	v_writelane_b32 v254, s64, 38
	s_nop 1
	v_writelane_b32 v254, s65, 39
	v_writelane_b32 v254, s26, 40
	s_nop 1
	v_writelane_b32 v254, s27, 41
	v_writelane_b32 v254, s96, 42
	s_nop 1
	v_writelane_b32 v254, s97, 43
	s_branch .LBB0_190

.LBB0_225:
	s_andn2_saveexec_b64 s[2:3], s[6:7]
	s_cbranch_execz .LBB0_245
	s_mov_b64 s[6:7], exec
	v_readlane_b32 s2, v255, 12
	s_cmp_lg_u32 s2, 0
	s_cbranch_scc1 .Lxb_local_0
	buffer_wbl2 sc1
	s_waitcnt lgkmcnt(0)
	s_waitcnt vmcnt(0)
	v_mbcnt_lo_u32_b32 v1, s6, 0
	v_mbcnt_hi_u32_b32 v1, s7, v1
	v_cmp_eq_u32_e32 vcc, 0, v1
	s_and_saveexec_b64 s[8:9], vcc
	s_cbranch_execz .LBB0_228
	s_bcnt1_i32_b64 s2, s[6:7]
	v_mov_b32_e32 v2, s2
	v_readlane_b32 s2, v253, 40
	v_readlane_b32 s3, v253, 41
	s_nop 4
	global_atomic_add v2, v197, v2, s[2:3] sc0

.LBB0_828:
	s_andn2_saveexec_b64 s[2:3], s[12:13]
	s_cbranch_execz .LBB0_848
	s_mov_b64 s[12:13], exec
	v_readlane_b32 s2, v255, 12
	s_cmp_lg_u32 s2, 0
	s_cbranch_scc1 .Lxb_local_5
	buffer_wbl2 sc1
	s_waitcnt lgkmcnt(0)
	s_waitcnt vmcnt(0)
	v_mbcnt_lo_u32_b32 v1, s12, 0
	v_mbcnt_hi_u32_b32 v1, s13, v1
	v_cmp_eq_u32_e32 vcc, 0, v1
	s_and_saveexec_b64 s[14:15], vcc
	s_cbranch_execz .LBB0_831
	s_bcnt1_i32_b64 s2, s[12:13]
	v_mov_b32_e32 v2, s2
	v_readlane_b32 s2, v253, 40
	v_readlane_b32 s3, v253, 41
	s_nop 4
	global_atomic_add v2, v197, v2, s[2:3] sc0

.LBB0_885:
	s_andn2_saveexec_b64 s[12:13], s[12:13]
	s_cbranch_execz .LBB0_905
	s_mov_b64 s[14:15], exec
	v_readlane_b32 s2, v255, 12
	s_cmp_lg_u32 s2, 0
	s_cbranch_scc1 .Lxb_local_6
	buffer_wbl2 sc1
	s_waitcnt lgkmcnt(0)
	s_waitcnt vmcnt(0)
	v_mbcnt_lo_u32_b32 v1, s14, 0
	v_mbcnt_hi_u32_b32 v1, s15, v1
	v_cmp_eq_u32_e32 vcc, 0, v1
	s_and_saveexec_b64 s[16:17], vcc
	s_cbranch_execz .LBB0_888
	s_bcnt1_i32_b64 s2, s[14:15]
	v_mov_b32_e32 v2, s2
	v_readlane_b32 s2, v253, 40
	v_readlane_b32 s3, v253, 41
	s_nop 4
	global_atomic_add v2, v197, v2, s[2:3] sc0
